# P1 latent-row norm loop and final rmsnorm loop hand-pipelined like P7 (3 row buffers, counted vmcnt)
# baseline (speedup 1.0000x reference)
; __device__ __forceinline__ unsigned cvt_pk_bf16(float lo, float hi) { unsigned r; asm volatile("v_cvt_pk_bf16_f32 %0, %1, %2" : "=v"(r) : "v"(lo), "v"(hi)); return r; }
; #define xlat_in ((l == 0) ? IN(I_X) : OUTP)
; #define xctx_in ((l == 0) ? IN(I_CTX) : CX)
; __device__ __forceinline__ void norm_row_mod(const float* xrow, const float* sh, const float* sc, bf16_t* orow, int lane) {
;     const f32x4* xr = (const f32x4*)xrow + lane;
;     f32x4 v[4]; float s = 0.f;
; #pragma unroll
;     for (int j = 0; j < 4; ++j) { v[j] = xr[64 * j]; s += (v[j].x * v[j].x + v[j].y * v[j].y) + (v[j].z * v[j].z + v[j].w * v[j].w); }
;     const float rstd = rsqrtf(wave_sum(s, lane) * (1.f / DM) + EPS);
;     u32x2* o8 = (u32x2*)orow + lane;
; #pragma unroll
;     for (int j = 0; j < 4; ++j) { const f32x4 a = ((const f32x4*)sh)[lane + 64 * j], b = ((const f32x4*)sc)[lane + 64 * j];
;         const f32x4 y = v[j] * rstd * (b + 1.0f) + a;
;         u32x2 w; w.x = cvt_pk_bf16(y.x, y.y); w.y = cvt_pk_bf16(y.z, y.w); o8[64 * j] = w; }
; }
; __global__ void __launch_bounds__(512, 2) mega_fwd(Args a) {
;     ...
;             for (int m = gw; m < TT; m += NGW) {
;                 const bool isl = m < TL; const int j = isl ? (m >> 12) : 8;
;                 if (!isl && l > 0) {
;                     f32x4* cr = (f32x4*)(CX + (size_t)(m - TL) * DM) + lane;
;                     const f32x4* pr = (const f32x4*)((const float*)(ws + WS_KVM) + (size_t)(m - TL) * DM) + lane;
;                     const f32x4* gp = (const f32x4*)(MOD + (size_t)(l - 1) * 9 * NMOD + (size_t)8 * NMOD + 5 * DM) + lane;
; #pragma unroll
;                     for (int jj = 0; jj < 4; ++jj) {
;                         const f32x4 p = (pr[64 * jj] + pr[64 * jj + (size_t)TC * DM / 4]) + (pr[64 * jj + 2 * (size_t)TC * DM / 4] + pr[64 * jj + 3 * (size_t)TC * DM / 4]);
;                         cr[64 * jj] = cr[64 * jj] + gp[64 * jj] * p;
;                     }
;                     asm volatile("s_waitcnt vmcnt(0)" ::: "memory");
;                 }
;                 const float* xr = isl ? xlat_in + (size_t)m * DM : xctx_in + (size_t)(m - TL) * DM;
;                 norm_row_mod(xr, modl + (size_t)j * NMOD + 0 * DM, modl + (size_t)j * NMOD + 1 * DM, XN + (size_t)m * DM, lane);
;             }
.LBB0_89:
	s_or_b64 exec, exec, s[8:9]
	s_cmp_gt_i32 s4, 0x87ff
	s_mul_i32 s66, s86, 0xd800
	s_cbranch_scc1 .LBB0_100
	v_add_co_u32_e64 v8, s[8:9], s86, -1
	v_ashrrev_i32_e32 v5, 31, v4
	s_mov_b32 s5, 0x36000
	s_waitcnt lgkmcnt(0)
	s_add_u32 s10, s6, 0x1900000
	v_lshlrev_b64 v[0:1], 4, v[4:5]
	v_mul_hi_u32 v9, v8, s5
	v_mul_lo_u32 v8, v8, s5
	s_addc_u32 s11, s7, 0
	v_lshl_add_u64 v[6:7], s[6:7], 0, v[0:1]
	s_mov_b64 s[12:13], 0x19000000
	v_lshl_add_u64 v[8:9], s[6:7], 0, v[8:9]
	v_lshl_add_u64 v[6:7], v[6:7], 0, s[12:13]
	v_lshl_add_u64 v[8:9], v[8:9], 0, v[0:1]
	s_mov_b64 s[12:13], 0x35000
	s_cmp_eq_u32 s86, 0
	v_lshl_add_u64 v[8:9], v[8:9], 0, s[12:13]
	s_cselect_b64 s[12:13], -1, 0
	s_and_b64 s[14:15], s[12:13], exec
	s_mov_b32 s67, s79
	s_cselect_b32 s18, 0, 0xc0
	s_lshl_b64 s[14:15], s[66:67], 2
	s_add_u32 s19, s6, s14
	s_addc_u32 s20, s7, s15
	v_lshlrev_b32_e32 v15, 2, v4
	v_lshl_add_u64 v[4:5], v[4:5], 3, s[6:7]
	s_mov_b64 s[6:7], 0x3c00000
	s_ashr_i32 s5, s4, 31
	v_lshl_add_u64 v[2:3], s[10:11], 0, v[0:1]
	v_xor_b32_e32 v10, 4, v15
	v_xor_b32_e32 v11, 8, v15
	v_xor_b32_e32 v12, 16, v15
	v_xor_b32_e32 v13, 32, v15
	v_xor_b32_e32 v14, 64, v15
	v_xor_b32_e32 v15, 0x80, v15
	v_lshl_add_u64 v[4:5], v[4:5], 0, s[6:7]
	s_lshl_b64 s[6:7], s[4:5], 12
	s_cmp_lt_i32 s4, 0x8000
	s_cbranch_scc0 .Lp1_skip
	s_add_u32 s14, s0, s18
	s_addc_u32 s15, s1, 0
	s_load_dwordx2 s[26:27], s[14:15], 0x0
	s_waitcnt lgkmcnt(0)
	s_mov_b32 s14, s4
	s_mov_b32 s15, 0
	s_lshl_b64 s[14:15], s[14:15], 12
	s_add_u32 s14, s14, s26
	s_addc_u32 s15, s15, s27
	v_lshl_add_u64 v[18:19], s[14:15], 0, v[0:1]
	global_load_dwordx4 v[64:67], v[18:19], off
	global_load_dwordx4 v[68:71], v[18:19], off offset:1024
	global_load_dwordx4 v[72:75], v[18:19], off offset:2048
	global_load_dwordx4 v[76:79], v[18:19], off offset:3072
	s_add_i32 s21, s4, s62
	s_cmp_lt_i32 s21, 0x8000
	s_cselect_b32 s21, s21, s4
	s_mov_b32 s14, s21
	s_mov_b32 s15, 0
	s_lshl_b64 s[14:15], s[14:15], 12
	s_add_u32 s14, s14, s26
	s_addc_u32 s15, s15, s27
	v_lshl_add_u64 v[18:19], s[14:15], 0, v[0:1]
	global_load_dwordx4 v[80:83], v[18:19], off
	global_load_dwordx4 v[84:87], v[18:19], off offset:1024
	global_load_dwordx4 v[88:91], v[18:19], off offset:2048
	global_load_dwordx4 v[92:95], v[18:19], off offset:3072
	s_ashr_i32 s21, s4, 12
	s_mul_i32 s21, s21, 0x6000
	s_add_u32 s14, s19, s21
	s_addc_u32 s15, s20, 0
	s_add_u32 s14, s14, 0x1000
	s_addc_u32 s15, s15, 0
	v_lshl_add_u64 v[16:17], s[14:15], 0, v[0:1]
	global_load_dwordx4 v[164:167], v[16:17], off offset:-4096
	global_load_dwordx4 v[168:171], v[16:17], off offset:-3072
	global_load_dwordx4 v[172:175], v[16:17], off offset:-2048
	global_load_dwordx4 v[176:179], v[16:17], off offset:-1024
	global_load_dwordx4 v[180:183], v[16:17], off
	global_load_dwordx4 v[184:187], v[16:17], off offset:1024
	global_load_dwordx4 v[188:191], v[16:17], off offset:2048
	global_load_dwordx4 v[192:195], v[16:17], off offset:3072
	s_add_i32 s21, s4, s62
	s_add_i32 s21, s21, s62
	s_cmp_lt_i32 s21, 0x8000
	s_cselect_b32 s21, s21, s4
	s_mov_b32 s14, s21
	s_mov_b32 s15, 0
	s_lshl_b64 s[14:15], s[14:15], 12
	s_add_u32 s14, s14, s26
	s_addc_u32 s15, s15, s27
	v_lshl_add_u64 v[18:19], s[14:15], 0, v[0:1]
	global_load_dwordx4 v[96:99], v[18:19], off
	global_load_dwordx4 v[100:103], v[18:19], off offset:1024
	global_load_dwordx4 v[104:107], v[18:19], off offset:2048
	global_load_dwordx4 v[108:111], v[18:19], off offset:3072
	s_mov_b32 s14, s4
	s_mov_b32 s15, 0
	s_lshl_b64 s[14:15], s[14:15], 11
	v_lshl_add_u64 v[20:21], v[4:5], 0, s[14:15]
	s_waitcnt vmcnt(16)
	v_pk_mul_f32 v[22:23], v[64:65], v[64:65]
	v_pk_fma_f32 v[22:23], v[66:67], v[66:67], v[22:23]
	v_pk_fma_f32 v[22:23], v[68:69], v[68:69], v[22:23]
	v_pk_fma_f32 v[22:23], v[70:71], v[70:71], v[22:23]
	v_pk_fma_f32 v[22:23], v[72:73], v[72:73], v[22:23]
	v_pk_fma_f32 v[22:23], v[74:75], v[74:75], v[22:23]
	v_pk_fma_f32 v[22:23], v[76:77], v[76:77], v[22:23]
	v_pk_fma_f32 v[22:23], v[78:79], v[78:79], v[22:23]
	s_nop 0
	v_add_f32_e32 v22, v22, v23
	ds_bpermute_b32 v26, v10, v22
	s_waitcnt lgkmcnt(0)
	v_add_f32_e32 v22, v22, v26
	ds_bpermute_b32 v26, v11, v22
	s_waitcnt lgkmcnt(0)
	v_add_f32_e32 v22, v22, v26
	ds_bpermute_b32 v26, v12, v22
	s_waitcnt lgkmcnt(0)
	v_add_f32_e32 v22, v22, v26
	ds_bpermute_b32 v26, v13, v22
	s_waitcnt lgkmcnt(0)
	v_add_f32_e32 v22, v22, v26
	ds_bpermute_b32 v26, v14, v22
	s_waitcnt lgkmcnt(0)
	v_add_f32_e32 v22, v22, v26
	ds_bpermute_b32 v26, v15, v22
	s_waitcnt lgkmcnt(0)
	v_add_f32_e32 v22, v22, v26
	v_fmamk_f32 v22, v22, 0x3a800000, v205
	v_mul_f32_e32 v26, 0x4b800000, v22
	v_cmp_gt_f32_e32 vcc, s2, v22
	s_nop 1
	v_cndmask_b32_e32 v22, v22, v26, vcc
	v_rsq_f32_e32 v22, v22
	s_nop 0
	v_mul_f32_e32 v26, 0x45800000, v22
	v_cndmask_b32_e32 v24, v22, v26, vcc
	s_waitcnt vmcnt(4)
	v_pk_mul_f32 v[64:65], v[64:65], v[24:25] op_sel_hi:[1,0]
	v_pk_mul_f32 v[66:67], v[66:67], v[24:25] op_sel_hi:[1,0]
	v_pk_add_f32 v[180:181], v[180:181], 1.0 op_sel_hi:[1,0]
	v_pk_add_f32 v[182:183], v[182:183], 1.0 op_sel_hi:[1,0]
	v_pk_fma_f32 v[64:65], v[180:181], v[64:65], v[164:165]
	v_pk_fma_f32 v[66:67], v[182:183], v[66:67], v[166:167]
	v_cvt_pk_bf16_f32 v64, v64, v65
	v_cvt_pk_bf16_f32 v65, v66, v67
	global_store_dwordx2 v[20:21], v[64:65], off
	v_pk_mul_f32 v[68:69], v[68:69], v[24:25] op_sel_hi:[1,0]
	v_pk_mul_f32 v[70:71], v[70:71], v[24:25] op_sel_hi:[1,0]
	v_pk_add_f32 v[184:185], v[184:185], 1.0 op_sel_hi:[1,0]
	v_pk_add_f32 v[186:187], v[186:187], 1.0 op_sel_hi:[1,0]
	v_pk_fma_f32 v[68:69], v[184:185], v[68:69], v[168:169]
	v_pk_fma_f32 v[70:71], v[186:187], v[70:71], v[170:171]
	v_cvt_pk_bf16_f32 v68, v68, v69
	v_cvt_pk_bf16_f32 v69, v70, v71
	global_store_dwordx2 v[20:21], v[68:69], off offset:512
	v_pk_mul_f32 v[72:73], v[72:73], v[24:25] op_sel_hi:[1,0]
	v_pk_mul_f32 v[74:75], v[74:75], v[24:25] op_sel_hi:[1,0]
	v_pk_add_f32 v[188:189], v[188:189], 1.0 op_sel_hi:[1,0]
	v_pk_add_f32 v[190:191], v[190:191], 1.0 op_sel_hi:[1,0]
	v_pk_fma_f32 v[72:73], v[188:189], v[72:73], v[172:173]
	v_pk_fma_f32 v[74:75], v[190:191], v[74:75], v[174:175]
	v_cvt_pk_bf16_f32 v72, v72, v73
	v_cvt_pk_bf16_f32 v73, v74, v75
	global_store_dwordx2 v[20:21], v[72:73], off offset:1024
	v_pk_mul_f32 v[76:77], v[76:77], v[24:25] op_sel_hi:[1,0]
	v_pk_mul_f32 v[78:79], v[78:79], v[24:25] op_sel_hi:[1,0]
	v_pk_add_f32 v[192:193], v[192:193], 1.0 op_sel_hi:[1,0]
	v_pk_add_f32 v[194:195], v[194:195], 1.0 op_sel_hi:[1,0]
	v_pk_fma_f32 v[76:77], v[192:193], v[76:77], v[176:177]
	v_pk_fma_f32 v[78:79], v[194:195], v[78:79], v[178:179]
	v_cvt_pk_bf16_f32 v76, v76, v77
	v_cvt_pk_bf16_f32 v77, v78, v79
	global_store_dwordx2 v[20:21], v[76:77], off offset:1536
	s_add_i32 s4, s4, s62
	s_cmp_ge_i32 s4, 0x8000
	s_cbranch_scc1 .Lp1_done
; __device__ __forceinline__ unsigned cvt_pk_bf16(float lo, float hi) { unsigned r; asm volatile("v_cvt_pk_bf16_f32 %0, %1, %2" : "=v"(r) : "v"(lo), "v"(hi)); return r; }
; #define xlat_in ((l == 0) ? IN(I_X) : OUTP)
; #define xctx_in ((l == 0) ? IN(I_CTX) : CX)
; __device__ __forceinline__ void norm_row_mod(const float* xrow, const float* sh, const float* sc, bf16_t* orow, int lane) {
;     const f32x4* xr = (const f32x4*)xrow + lane;
;     f32x4 v[4]; float s = 0.f;
; #pragma unroll
;     for (int j = 0; j < 4; ++j) { v[j] = xr[64 * j]; s += (v[j].x * v[j].x + v[j].y * v[j].y) + (v[j].z * v[j].z + v[j].w * v[j].w); }
;     const float rstd = rsqrtf(wave_sum(s, lane) * (1.f / DM) + EPS);
;     u32x2* o8 = (u32x2*)orow + lane;
; #pragma unroll
;     for (int j = 0; j < 4; ++j) { const f32x4 a = ((const f32x4*)sh)[lane + 64 * j], b = ((const f32x4*)sc)[lane + 64 * j];
;         const f32x4 y = v[j] * rstd * (b + 1.0f) + a;
;         u32x2 w; w.x = cvt_pk_bf16(y.x, y.y); w.y = cvt_pk_bf16(y.z, y.w); o8[64 * j] = w; }
; }
; __global__ void __launch_bounds__(512, 2) mega_fwd(Args a) {
;     ...
;             for (int m = gw; m < TT; m += NGW) {
;                 const bool isl = m < TL; const int j = isl ? (m >> 12) : 8;
;                 if (!isl && l > 0) {
;                     f32x4* cr = (f32x4*)(CX + (size_t)(m - TL) * DM) + lane;
;                     const f32x4* pr = (const f32x4*)((const float*)(ws + WS_KVM) + (size_t)(m - TL) * DM) + lane;
;                     const f32x4* gp = (const f32x4*)(MOD + (size_t)(l - 1) * 9 * NMOD + (size_t)8 * NMOD + 5 * DM) + lane;
; #pragma unroll
;                     for (int jj = 0; jj < 4; ++jj) {
;                         const f32x4 p = (pr[64 * jj] + pr[64 * jj + (size_t)TC * DM / 4]) + (pr[64 * jj + 2 * (size_t)TC * DM / 4] + pr[64 * jj + 3 * (size_t)TC * DM / 4]);
;                         cr[64 * jj] = cr[64 * jj] + gp[64 * jj] * p;
;                     }
;                     asm volatile("s_waitcnt vmcnt(0)" ::: "memory");
;                 }
;                 const float* xr = isl ? xlat_in + (size_t)m * DM : xctx_in + (size_t)(m - TL) * DM;
;                 norm_row_mod(xr, modl + (size_t)j * NMOD + 0 * DM, modl + (size_t)j * NMOD + 1 * DM, XN + (size_t)m * DM, lane);
	s_ashr_i32 s21, s4, 12
	s_mul_i32 s21, s21, 0x6000
	s_add_u32 s14, s19, s21
	s_addc_u32 s15, s20, 0
	s_add_u32 s14, s14, 0x1000
	s_addc_u32 s15, s15, 0
	v_lshl_add_u64 v[16:17], s[14:15], 0, v[0:1]
	global_load_dwordx4 v[164:167], v[16:17], off offset:-4096
	global_load_dwordx4 v[168:171], v[16:17], off offset:-3072
	global_load_dwordx4 v[172:175], v[16:17], off offset:-2048
	global_load_dwordx4 v[176:179], v[16:17], off offset:-1024
	global_load_dwordx4 v[180:183], v[16:17], off
	global_load_dwordx4 v[184:187], v[16:17], off offset:1024
	global_load_dwordx4 v[188:191], v[16:17], off offset:2048
	global_load_dwordx4 v[192:195], v[16:17], off offset:3072
	s_add_i32 s21, s4, s62
	s_add_i32 s21, s21, s62
	s_cmp_lt_i32 s21, 0x8000
	s_cselect_b32 s21, s21, s4
	s_mov_b32 s14, s21
	s_mov_b32 s15, 0
	s_lshl_b64 s[14:15], s[14:15], 12
	s_add_u32 s14, s14, s26
	s_addc_u32 s15, s15, s27
	v_lshl_add_u64 v[18:19], s[14:15], 0, v[0:1]
	global_load_dwordx4 v[64:67], v[18:19], off
	global_load_dwordx4 v[68:71], v[18:19], off offset:1024
	global_load_dwordx4 v[72:75], v[18:19], off offset:2048
	global_load_dwordx4 v[76:79], v[18:19], off offset:3072
	s_mov_b32 s14, s4
	s_mov_b32 s15, 0
	s_lshl_b64 s[14:15], s[14:15], 11
	v_lshl_add_u64 v[20:21], v[4:5], 0, s[14:15]
	s_waitcnt vmcnt(28)
	v_pk_mul_f32 v[22:23], v[80:81], v[80:81]
	v_pk_fma_f32 v[22:23], v[82:83], v[82:83], v[22:23]
	v_pk_fma_f32 v[22:23], v[84:85], v[84:85], v[22:23]
	v_pk_fma_f32 v[22:23], v[86:87], v[86:87], v[22:23]
	v_pk_fma_f32 v[22:23], v[88:89], v[88:89], v[22:23]
	v_pk_fma_f32 v[22:23], v[90:91], v[90:91], v[22:23]
	v_pk_fma_f32 v[22:23], v[92:93], v[92:93], v[22:23]
	v_pk_fma_f32 v[22:23], v[94:95], v[94:95], v[22:23]
	s_nop 0
	v_add_f32_e32 v22, v22, v23
	ds_bpermute_b32 v26, v10, v22
	s_waitcnt lgkmcnt(0)
	v_add_f32_e32 v22, v22, v26
	ds_bpermute_b32 v26, v11, v22
	s_waitcnt lgkmcnt(0)
	v_add_f32_e32 v22, v22, v26
	ds_bpermute_b32 v26, v12, v22
	s_waitcnt lgkmcnt(0)
	v_add_f32_e32 v22, v22, v26
	ds_bpermute_b32 v26, v13, v22
	s_waitcnt lgkmcnt(0)
	v_add_f32_e32 v22, v22, v26
	ds_bpermute_b32 v26, v14, v22
	s_waitcnt lgkmcnt(0)
	v_add_f32_e32 v22, v22, v26
	ds_bpermute_b32 v26, v15, v22
	s_waitcnt lgkmcnt(0)
	v_add_f32_e32 v22, v22, v26
	v_fmamk_f32 v22, v22, 0x3a800000, v205
	v_mul_f32_e32 v26, 0x4b800000, v22
	v_cmp_gt_f32_e32 vcc, s2, v22
	s_nop 1
	v_cndmask_b32_e32 v22, v22, v26, vcc
	v_rsq_f32_e32 v22, v22
	s_nop 0
	v_mul_f32_e32 v26, 0x45800000, v22
	v_cndmask_b32_e32 v24, v22, v26, vcc
	s_waitcnt vmcnt(4)
	v_pk_mul_f32 v[80:81], v[80:81], v[24:25] op_sel_hi:[1,0]
	v_pk_mul_f32 v[82:83], v[82:83], v[24:25] op_sel_hi:[1,0]
	v_pk_add_f32 v[180:181], v[180:181], 1.0 op_sel_hi:[1,0]
	v_pk_add_f32 v[182:183], v[182:183], 1.0 op_sel_hi:[1,0]
	v_pk_fma_f32 v[80:81], v[180:181], v[80:81], v[164:165]
	v_pk_fma_f32 v[82:83], v[182:183], v[82:83], v[166:167]
	v_cvt_pk_bf16_f32 v80, v80, v81
	v_cvt_pk_bf16_f32 v81, v82, v83
	global_store_dwordx2 v[20:21], v[80:81], off
	v_pk_mul_f32 v[84:85], v[84:85], v[24:25] op_sel_hi:[1,0]
	v_pk_mul_f32 v[86:87], v[86:87], v[24:25] op_sel_hi:[1,0]
	v_pk_add_f32 v[184:185], v[184:185], 1.0 op_sel_hi:[1,0]
	v_pk_add_f32 v[186:187], v[186:187], 1.0 op_sel_hi:[1,0]
	v_pk_fma_f32 v[84:85], v[184:185], v[84:85], v[168:169]
	v_pk_fma_f32 v[86:87], v[186:187], v[86:87], v[170:171]
	v_cvt_pk_bf16_f32 v84, v84, v85
	v_cvt_pk_bf16_f32 v85, v86, v87
	global_store_dwordx2 v[20:21], v[84:85], off offset:512
	v_pk_mul_f32 v[88:89], v[88:89], v[24:25] op_sel_hi:[1,0]
	v_pk_mul_f32 v[90:91], v[90:91], v[24:25] op_sel_hi:[1,0]
	v_pk_add_f32 v[188:189], v[188:189], 1.0 op_sel_hi:[1,0]
	v_pk_add_f32 v[190:191], v[190:191], 1.0 op_sel_hi:[1,0]
	v_pk_fma_f32 v[88:89], v[188:189], v[88:89], v[172:173]
	v_pk_fma_f32 v[90:91], v[190:191], v[90:91], v[174:175]
	v_cvt_pk_bf16_f32 v88, v88, v89
	v_cvt_pk_bf16_f32 v89, v90, v91
	global_store_dwordx2 v[20:21], v[88:89], off offset:1024
	v_pk_mul_f32 v[92:93], v[92:93], v[24:25] op_sel_hi:[1,0]
	v_pk_mul_f32 v[94:95], v[94:95], v[24:25] op_sel_hi:[1,0]
	v_pk_add_f32 v[192:193], v[192:193], 1.0 op_sel_hi:[1,0]
	v_pk_add_f32 v[194:195], v[194:195], 1.0 op_sel_hi:[1,0]
	v_pk_fma_f32 v[92:93], v[192:193], v[92:93], v[176:177]
	v_pk_fma_f32 v[94:95], v[194:195], v[94:95], v[178:179]
	v_cvt_pk_bf16_f32 v92, v92, v93
	v_cvt_pk_bf16_f32 v93, v94, v95
	global_store_dwordx2 v[20:21], v[92:93], off offset:1536
	s_add_i32 s4, s4, s62
	s_cmp_ge_i32 s4, 0x8000
	s_cbranch_scc1 .Lp1_done
; __device__ __forceinline__ unsigned cvt_pk_bf16(float lo, float hi) { unsigned r; asm volatile("v_cvt_pk_bf16_f32 %0, %1, %2" : "=v"(r) : "v"(lo), "v"(hi)); return r; }
; #define xlat_in ((l == 0) ? IN(I_X) : OUTP)
; #define xctx_in ((l == 0) ? IN(I_CTX) : CX)
; __device__ __forceinline__ void norm_row_mod(const float* xrow, const float* sh, const float* sc, bf16_t* orow, int lane) {
;     const f32x4* xr = (const f32x4*)xrow + lane;
;     f32x4 v[4]; float s = 0.f;
; #pragma unroll
;     for (int j = 0; j < 4; ++j) { v[j] = xr[64 * j]; s += (v[j].x * v[j].x + v[j].y * v[j].y) + (v[j].z * v[j].z + v[j].w * v[j].w); }
;     const float rstd = rsqrtf(wave_sum(s, lane) * (1.f / DM) + EPS);
;     u32x2* o8 = (u32x2*)orow + lane;
; #pragma unroll
;     for (int j = 0; j < 4; ++j) { const f32x4 a = ((const f32x4*)sh)[lane + 64 * j], b = ((const f32x4*)sc)[lane + 64 * j];
;         const f32x4 y = v[j] * rstd * (b + 1.0f) + a;
;         u32x2 w; w.x = cvt_pk_bf16(y.x, y.y); w.y = cvt_pk_bf16(y.z, y.w); o8[64 * j] = w; }
; }
; __global__ void __launch_bounds__(512, 2) mega_fwd(Args a) {
;     ...
;             for (int m = gw; m < TT; m += NGW) {
;                 const bool isl = m < TL; const int j = isl ? (m >> 12) : 8;
;                 if (!isl && l > 0) {
;                     f32x4* cr = (f32x4*)(CX + (size_t)(m - TL) * DM) + lane;
;                     const f32x4* pr = (const f32x4*)((const float*)(ws + WS_KVM) + (size_t)(m - TL) * DM) + lane;
;                     const f32x4* gp = (const f32x4*)(MOD + (size_t)(l - 1) * 9 * NMOD + (size_t)8 * NMOD + 5 * DM) + lane;
; #pragma unroll
;                     for (int jj = 0; jj < 4; ++jj) {
;                         const f32x4 p = (pr[64 * jj] + pr[64 * jj + (size_t)TC * DM / 4]) + (pr[64 * jj + 2 * (size_t)TC * DM / 4] + pr[64 * jj + 3 * (size_t)TC * DM / 4]);
;                         cr[64 * jj] = cr[64 * jj] + gp[64 * jj] * p;
;                     }
;                     asm volatile("s_waitcnt vmcnt(0)" ::: "memory");
;                 }
;                 const float* xr = isl ? xlat_in + (size_t)m * DM : xctx_in + (size_t)(m - TL) * DM;
;                 norm_row_mod(xr, modl + (size_t)j * NMOD + 0 * DM, modl + (size_t)j * NMOD + 1 * DM, XN + (size_t)m * DM, lane);
.Lp1_loop:
	s_ashr_i32 s21, s4, 12
	s_mul_i32 s21, s21, 0x6000
	s_add_u32 s14, s19, s21
	s_addc_u32 s15, s20, 0
	s_add_u32 s14, s14, 0x1000
	s_addc_u32 s15, s15, 0
	v_lshl_add_u64 v[16:17], s[14:15], 0, v[0:1]
	global_load_dwordx4 v[164:167], v[16:17], off offset:-4096
	global_load_dwordx4 v[168:171], v[16:17], off offset:-3072
	global_load_dwordx4 v[172:175], v[16:17], off offset:-2048
	global_load_dwordx4 v[176:179], v[16:17], off offset:-1024
	global_load_dwordx4 v[180:183], v[16:17], off
	global_load_dwordx4 v[184:187], v[16:17], off offset:1024
	global_load_dwordx4 v[188:191], v[16:17], off offset:2048
	global_load_dwordx4 v[192:195], v[16:17], off offset:3072
	s_add_i32 s21, s4, s62
	s_add_i32 s21, s21, s62
	s_cmp_lt_i32 s21, 0x8000
	s_cselect_b32 s21, s21, s4
	s_mov_b32 s14, s21
	s_mov_b32 s15, 0
	s_lshl_b64 s[14:15], s[14:15], 12
	s_add_u32 s14, s14, s26
	s_addc_u32 s15, s15, s27
	v_lshl_add_u64 v[18:19], s[14:15], 0, v[0:1]
	global_load_dwordx4 v[80:83], v[18:19], off
	global_load_dwordx4 v[84:87], v[18:19], off offset:1024
	global_load_dwordx4 v[88:91], v[18:19], off offset:2048
	global_load_dwordx4 v[92:95], v[18:19], off offset:3072
	s_mov_b32 s14, s4
	s_mov_b32 s15, 0
	s_lshl_b64 s[14:15], s[14:15], 11
	v_lshl_add_u64 v[20:21], v[4:5], 0, s[14:15]
	s_waitcnt vmcnt(32)
	v_pk_mul_f32 v[22:23], v[96:97], v[96:97]
	v_pk_fma_f32 v[22:23], v[98:99], v[98:99], v[22:23]
	v_pk_fma_f32 v[22:23], v[100:101], v[100:101], v[22:23]
	v_pk_fma_f32 v[22:23], v[102:103], v[102:103], v[22:23]
	v_pk_fma_f32 v[22:23], v[104:105], v[104:105], v[22:23]
	v_pk_fma_f32 v[22:23], v[106:107], v[106:107], v[22:23]
	v_pk_fma_f32 v[22:23], v[108:109], v[108:109], v[22:23]
	v_pk_fma_f32 v[22:23], v[110:111], v[110:111], v[22:23]
	s_nop 0
	v_add_f32_e32 v22, v22, v23
	ds_bpermute_b32 v26, v10, v22
	s_waitcnt lgkmcnt(0)
	v_add_f32_e32 v22, v22, v26
	ds_bpermute_b32 v26, v11, v22
	s_waitcnt lgkmcnt(0)
	v_add_f32_e32 v22, v22, v26
	ds_bpermute_b32 v26, v12, v22
	s_waitcnt lgkmcnt(0)
	v_add_f32_e32 v22, v22, v26
	ds_bpermute_b32 v26, v13, v22
	s_waitcnt lgkmcnt(0)
	v_add_f32_e32 v22, v22, v26
	ds_bpermute_b32 v26, v14, v22
	s_waitcnt lgkmcnt(0)
	v_add_f32_e32 v22, v22, v26
	ds_bpermute_b32 v26, v15, v22
	s_waitcnt lgkmcnt(0)
	v_add_f32_e32 v22, v22, v26
	v_fmamk_f32 v22, v22, 0x3a800000, v205
	v_mul_f32_e32 v26, 0x4b800000, v22
	v_cmp_gt_f32_e32 vcc, s2, v22
	s_nop 1
	v_cndmask_b32_e32 v22, v22, v26, vcc
	v_rsq_f32_e32 v22, v22
	s_nop 0
	v_mul_f32_e32 v26, 0x45800000, v22
	v_cndmask_b32_e32 v24, v22, v26, vcc
	s_waitcnt vmcnt(4)
	v_pk_mul_f32 v[96:97], v[96:97], v[24:25] op_sel_hi:[1,0]
	v_pk_mul_f32 v[98:99], v[98:99], v[24:25] op_sel_hi:[1,0]
	v_pk_add_f32 v[180:181], v[180:181], 1.0 op_sel_hi:[1,0]
	v_pk_add_f32 v[182:183], v[182:183], 1.0 op_sel_hi:[1,0]
	v_pk_fma_f32 v[96:97], v[180:181], v[96:97], v[164:165]
	v_pk_fma_f32 v[98:99], v[182:183], v[98:99], v[166:167]
	v_cvt_pk_bf16_f32 v96, v96, v97
	v_cvt_pk_bf16_f32 v97, v98, v99
	global_store_dwordx2 v[20:21], v[96:97], off
	v_pk_mul_f32 v[100:101], v[100:101], v[24:25] op_sel_hi:[1,0]
	v_pk_mul_f32 v[102:103], v[102:103], v[24:25] op_sel_hi:[1,0]
	v_pk_add_f32 v[184:185], v[184:185], 1.0 op_sel_hi:[1,0]
	v_pk_add_f32 v[186:187], v[186:187], 1.0 op_sel_hi:[1,0]
	v_pk_fma_f32 v[100:101], v[184:185], v[100:101], v[168:169]
	v_pk_fma_f32 v[102:103], v[186:187], v[102:103], v[170:171]
	v_cvt_pk_bf16_f32 v100, v100, v101
	v_cvt_pk_bf16_f32 v101, v102, v103
	global_store_dwordx2 v[20:21], v[100:101], off offset:512
	v_pk_mul_f32 v[104:105], v[104:105], v[24:25] op_sel_hi:[1,0]
	v_pk_mul_f32 v[106:107], v[106:107], v[24:25] op_sel_hi:[1,0]
	v_pk_add_f32 v[188:189], v[188:189], 1.0 op_sel_hi:[1,0]
	v_pk_add_f32 v[190:191], v[190:191], 1.0 op_sel_hi:[1,0]
	v_pk_fma_f32 v[104:105], v[188:189], v[104:105], v[172:173]
	v_pk_fma_f32 v[106:107], v[190:191], v[106:107], v[174:175]
	v_cvt_pk_bf16_f32 v104, v104, v105
	v_cvt_pk_bf16_f32 v105, v106, v107
	global_store_dwordx2 v[20:21], v[104:105], off offset:1024
	v_pk_mul_f32 v[108:109], v[108:109], v[24:25] op_sel_hi:[1,0]
	v_pk_mul_f32 v[110:111], v[110:111], v[24:25] op_sel_hi:[1,0]
	v_pk_add_f32 v[192:193], v[192:193], 1.0 op_sel_hi:[1,0]
	v_pk_add_f32 v[194:195], v[194:195], 1.0 op_sel_hi:[1,0]
	v_pk_fma_f32 v[108:109], v[192:193], v[108:109], v[176:177]
	v_pk_fma_f32 v[110:111], v[194:195], v[110:111], v[178:179]
	v_cvt_pk_bf16_f32 v108, v108, v109
	v_cvt_pk_bf16_f32 v109, v110, v111
	global_store_dwordx2 v[20:21], v[108:109], off offset:1536
	s_add_i32 s4, s4, s62
	s_cmp_ge_i32 s4, 0x8000
	s_cbranch_scc1 .Lp1_done
; __device__ __forceinline__ unsigned cvt_pk_bf16(float lo, float hi) { unsigned r; asm volatile("v_cvt_pk_bf16_f32 %0, %1, %2" : "=v"(r) : "v"(lo), "v"(hi)); return r; }
; #define xlat_in ((l == 0) ? IN(I_X) : OUTP)
; #define xctx_in ((l == 0) ? IN(I_CTX) : CX)
; __device__ __forceinline__ void norm_row_mod(const float* xrow, const float* sh, const float* sc, bf16_t* orow, int lane) {
;     const f32x4* xr = (const f32x4*)xrow + lane;
;     f32x4 v[4]; float s = 0.f;
; #pragma unroll
;     for (int j = 0; j < 4; ++j) { v[j] = xr[64 * j]; s += (v[j].x * v[j].x + v[j].y * v[j].y) + (v[j].z * v[j].z + v[j].w * v[j].w); }
;     const float rstd = rsqrtf(wave_sum(s, lane) * (1.f / DM) + EPS);
;     u32x2* o8 = (u32x2*)orow + lane;
; #pragma unroll
;     for (int j = 0; j < 4; ++j) { const f32x4 a = ((const f32x4*)sh)[lane + 64 * j], b = ((const f32x4*)sc)[lane + 64 * j];
;         const f32x4 y = v[j] * rstd * (b + 1.0f) + a;
;         u32x2 w; w.x = cvt_pk_bf16(y.x, y.y); w.y = cvt_pk_bf16(y.z, y.w); o8[64 * j] = w; }
; }
; __global__ void __launch_bounds__(512, 2) mega_fwd(Args a) {
;     ...
;             for (int m = gw; m < TT; m += NGW) {
;                 const bool isl = m < TL; const int j = isl ? (m >> 12) : 8;
;                 if (!isl && l > 0) {
;                     f32x4* cr = (f32x4*)(CX + (size_t)(m - TL) * DM) + lane;
;                     const f32x4* pr = (const f32x4*)((const float*)(ws + WS_KVM) + (size_t)(m - TL) * DM) + lane;
;                     const f32x4* gp = (const f32x4*)(MOD + (size_t)(l - 1) * 9 * NMOD + (size_t)8 * NMOD + 5 * DM) + lane;
; #pragma unroll
;                     for (int jj = 0; jj < 4; ++jj) {
;                         const f32x4 p = (pr[64 * jj] + pr[64 * jj + (size_t)TC * DM / 4]) + (pr[64 * jj + 2 * (size_t)TC * DM / 4] + pr[64 * jj + 3 * (size_t)TC * DM / 4]);
;                         cr[64 * jj] = cr[64 * jj] + gp[64 * jj] * p;
;                     }
;                     asm volatile("s_waitcnt vmcnt(0)" ::: "memory");
;                 }
;                 const float* xr = isl ? xlat_in + (size_t)m * DM : xctx_in + (size_t)(m - TL) * DM;
;                 norm_row_mod(xr, modl + (size_t)j * NMOD + 0 * DM, modl + (size_t)j * NMOD + 1 * DM, XN + (size_t)m * DM, lane);
	s_ashr_i32 s21, s4, 12
	s_mul_i32 s21, s21, 0x6000
	s_add_u32 s14, s19, s21
	s_addc_u32 s15, s20, 0
	s_add_u32 s14, s14, 0x1000
	s_addc_u32 s15, s15, 0
	v_lshl_add_u64 v[16:17], s[14:15], 0, v[0:1]
	global_load_dwordx4 v[164:167], v[16:17], off offset:-4096
	global_load_dwordx4 v[168:171], v[16:17], off offset:-3072
	global_load_dwordx4 v[172:175], v[16:17], off offset:-2048
	global_load_dwordx4 v[176:179], v[16:17], off offset:-1024
	global_load_dwordx4 v[180:183], v[16:17], off
	global_load_dwordx4 v[184:187], v[16:17], off offset:1024
	global_load_dwordx4 v[188:191], v[16:17], off offset:2048
	global_load_dwordx4 v[192:195], v[16:17], off offset:3072
	s_add_i32 s21, s4, s62
	s_add_i32 s21, s21, s62
	s_cmp_lt_i32 s21, 0x8000
	s_cselect_b32 s21, s21, s4
	s_mov_b32 s14, s21
	s_mov_b32 s15, 0
	s_lshl_b64 s[14:15], s[14:15], 12
	s_add_u32 s14, s14, s26
	s_addc_u32 s15, s15, s27
	v_lshl_add_u64 v[18:19], s[14:15], 0, v[0:1]
	global_load_dwordx4 v[96:99], v[18:19], off
	global_load_dwordx4 v[100:103], v[18:19], off offset:1024
	global_load_dwordx4 v[104:107], v[18:19], off offset:2048
	global_load_dwordx4 v[108:111], v[18:19], off offset:3072
	s_mov_b32 s14, s4
	s_mov_b32 s15, 0
	s_lshl_b64 s[14:15], s[14:15], 11
	v_lshl_add_u64 v[20:21], v[4:5], 0, s[14:15]
	s_waitcnt vmcnt(32)
	v_pk_mul_f32 v[22:23], v[64:65], v[64:65]
	v_pk_fma_f32 v[22:23], v[66:67], v[66:67], v[22:23]
	v_pk_fma_f32 v[22:23], v[68:69], v[68:69], v[22:23]
	v_pk_fma_f32 v[22:23], v[70:71], v[70:71], v[22:23]
	v_pk_fma_f32 v[22:23], v[72:73], v[72:73], v[22:23]
	v_pk_fma_f32 v[22:23], v[74:75], v[74:75], v[22:23]
	v_pk_fma_f32 v[22:23], v[76:77], v[76:77], v[22:23]
	v_pk_fma_f32 v[22:23], v[78:79], v[78:79], v[22:23]
	s_nop 0
	v_add_f32_e32 v22, v22, v23
	ds_bpermute_b32 v26, v10, v22
	s_waitcnt lgkmcnt(0)
	v_add_f32_e32 v22, v22, v26
	ds_bpermute_b32 v26, v11, v22
	s_waitcnt lgkmcnt(0)
	v_add_f32_e32 v22, v22, v26
	ds_bpermute_b32 v26, v12, v22
	s_waitcnt lgkmcnt(0)
	v_add_f32_e32 v22, v22, v26
	ds_bpermute_b32 v26, v13, v22
	s_waitcnt lgkmcnt(0)
	v_add_f32_e32 v22, v22, v26
	ds_bpermute_b32 v26, v14, v22
	s_waitcnt lgkmcnt(0)
	v_add_f32_e32 v22, v22, v26
	ds_bpermute_b32 v26, v15, v22
	s_waitcnt lgkmcnt(0)
	v_add_f32_e32 v22, v22, v26
	v_fmamk_f32 v22, v22, 0x3a800000, v205
	v_mul_f32_e32 v26, 0x4b800000, v22
	v_cmp_gt_f32_e32 vcc, s2, v22
	s_nop 1
	v_cndmask_b32_e32 v22, v22, v26, vcc
	v_rsq_f32_e32 v22, v22
	s_nop 0
	v_mul_f32_e32 v26, 0x45800000, v22
	v_cndmask_b32_e32 v24, v22, v26, vcc
	s_waitcnt vmcnt(4)
	v_pk_mul_f32 v[64:65], v[64:65], v[24:25] op_sel_hi:[1,0]
	v_pk_mul_f32 v[66:67], v[66:67], v[24:25] op_sel_hi:[1,0]
	v_pk_add_f32 v[180:181], v[180:181], 1.0 op_sel_hi:[1,0]
	v_pk_add_f32 v[182:183], v[182:183], 1.0 op_sel_hi:[1,0]
	v_pk_fma_f32 v[64:65], v[180:181], v[64:65], v[164:165]
	v_pk_fma_f32 v[66:67], v[182:183], v[66:67], v[166:167]
	v_cvt_pk_bf16_f32 v64, v64, v65
	v_cvt_pk_bf16_f32 v65, v66, v67
	global_store_dwordx2 v[20:21], v[64:65], off
	v_pk_mul_f32 v[68:69], v[68:69], v[24:25] op_sel_hi:[1,0]
	v_pk_mul_f32 v[70:71], v[70:71], v[24:25] op_sel_hi:[1,0]
	v_pk_add_f32 v[184:185], v[184:185], 1.0 op_sel_hi:[1,0]
	v_pk_add_f32 v[186:187], v[186:187], 1.0 op_sel_hi:[1,0]
	v_pk_fma_f32 v[68:69], v[184:185], v[68:69], v[168:169]
	v_pk_fma_f32 v[70:71], v[186:187], v[70:71], v[170:171]
	v_cvt_pk_bf16_f32 v68, v68, v69
	v_cvt_pk_bf16_f32 v69, v70, v71
	global_store_dwordx2 v[20:21], v[68:69], off offset:512
	v_pk_mul_f32 v[72:73], v[72:73], v[24:25] op_sel_hi:[1,0]
	v_pk_mul_f32 v[74:75], v[74:75], v[24:25] op_sel_hi:[1,0]
	v_pk_add_f32 v[188:189], v[188:189], 1.0 op_sel_hi:[1,0]
	v_pk_add_f32 v[190:191], v[190:191], 1.0 op_sel_hi:[1,0]
	v_pk_fma_f32 v[72:73], v[188:189], v[72:73], v[172:173]
	v_pk_fma_f32 v[74:75], v[190:191], v[74:75], v[174:175]
	v_cvt_pk_bf16_f32 v72, v72, v73
	v_cvt_pk_bf16_f32 v73, v74, v75
	global_store_dwordx2 v[20:21], v[72:73], off offset:1024
	v_pk_mul_f32 v[76:77], v[76:77], v[24:25] op_sel_hi:[1,0]
	v_pk_mul_f32 v[78:79], v[78:79], v[24:25] op_sel_hi:[1,0]
	v_pk_add_f32 v[192:193], v[192:193], 1.0 op_sel_hi:[1,0]
	v_pk_add_f32 v[194:195], v[194:195], 1.0 op_sel_hi:[1,0]
	v_pk_fma_f32 v[76:77], v[192:193], v[76:77], v[176:177]
	v_pk_fma_f32 v[78:79], v[194:195], v[78:79], v[178:179]
	v_cvt_pk_bf16_f32 v76, v76, v77
	v_cvt_pk_bf16_f32 v77, v78, v79
	global_store_dwordx2 v[20:21], v[76:77], off offset:1536
	s_add_i32 s4, s4, s62
	s_cmp_ge_i32 s4, 0x8000
	s_cbranch_scc1 .Lp1_done
; __device__ __forceinline__ unsigned cvt_pk_bf16(float lo, float hi) { unsigned r; asm volatile("v_cvt_pk_bf16_f32 %0, %1, %2" : "=v"(r) : "v"(lo), "v"(hi)); return r; }
; #define xlat_in ((l == 0) ? IN(I_X) : OUTP)
; #define xctx_in ((l == 0) ? IN(I_CTX) : CX)
; __device__ __forceinline__ void norm_row_mod(const float* xrow, const float* sh, const float* sc, bf16_t* orow, int lane) {
;     const f32x4* xr = (const f32x4*)xrow + lane;
;     f32x4 v[4]; float s = 0.f;
; #pragma unroll
;     for (int j = 0; j < 4; ++j) { v[j] = xr[64 * j]; s += (v[j].x * v[j].x + v[j].y * v[j].y) + (v[j].z * v[j].z + v[j].w * v[j].w); }
;     const float rstd = rsqrtf(wave_sum(s, lane) * (1.f / DM) + EPS);
;     u32x2* o8 = (u32x2*)orow + lane;
; #pragma unroll
;     for (int j = 0; j < 4; ++j) { const f32x4 a = ((const f32x4*)sh)[lane + 64 * j], b = ((const f32x4*)sc)[lane + 64 * j];
;         const f32x4 y = v[j] * rstd * (b + 1.0f) + a;
;         u32x2 w; w.x = cvt_pk_bf16(y.x, y.y); w.y = cvt_pk_bf16(y.z, y.w); o8[64 * j] = w; }
; }
; __global__ void __launch_bounds__(512, 2) mega_fwd(Args a) {
;     ...
;             for (int m = gw; m < TT; m += NGW) {
;                 const bool isl = m < TL; const int j = isl ? (m >> 12) : 8;
;                 if (!isl && l > 0) {
;                     f32x4* cr = (f32x4*)(CX + (size_t)(m - TL) * DM) + lane;
;                     const f32x4* pr = (const f32x4*)((const float*)(ws + WS_KVM) + (size_t)(m - TL) * DM) + lane;
;                     const f32x4* gp = (const f32x4*)(MOD + (size_t)(l - 1) * 9 * NMOD + (size_t)8 * NMOD + 5 * DM) + lane;
; #pragma unroll
;                     for (int jj = 0; jj < 4; ++jj) {
;                         const f32x4 p = (pr[64 * jj] + pr[64 * jj + (size_t)TC * DM / 4]) + (pr[64 * jj + 2 * (size_t)TC * DM / 4] + pr[64 * jj + 3 * (size_t)TC * DM / 4]);
;                         cr[64 * jj] = cr[64 * jj] + gp[64 * jj] * p;
;                     }
;                     asm volatile("s_waitcnt vmcnt(0)" ::: "memory");
;                 }
;                 const float* xr = isl ? xlat_in + (size_t)m * DM : xctx_in + (size_t)(m - TL) * DM;
;                 norm_row_mod(xr, modl + (size_t)j * NMOD + 0 * DM, modl + (size_t)j * NMOD + 1 * DM, XN + (size_t)m * DM, lane);
;             }
	s_ashr_i32 s21, s4, 12
	s_mul_i32 s21, s21, 0x6000
	s_add_u32 s14, s19, s21
	s_addc_u32 s15, s20, 0
	s_add_u32 s14, s14, 0x1000
	s_addc_u32 s15, s15, 0
	v_lshl_add_u64 v[16:17], s[14:15], 0, v[0:1]
	global_load_dwordx4 v[164:167], v[16:17], off offset:-4096
	global_load_dwordx4 v[168:171], v[16:17], off offset:-3072
	global_load_dwordx4 v[172:175], v[16:17], off offset:-2048
	global_load_dwordx4 v[176:179], v[16:17], off offset:-1024
	global_load_dwordx4 v[180:183], v[16:17], off
	global_load_dwordx4 v[184:187], v[16:17], off offset:1024
	global_load_dwordx4 v[188:191], v[16:17], off offset:2048
	global_load_dwordx4 v[192:195], v[16:17], off offset:3072
	s_add_i32 s21, s4, s62
	s_add_i32 s21, s21, s62
	s_cmp_lt_i32 s21, 0x8000
	s_cselect_b32 s21, s21, s4
	s_mov_b32 s14, s21
	s_mov_b32 s15, 0
	s_lshl_b64 s[14:15], s[14:15], 12
	s_add_u32 s14, s14, s26
	s_addc_u32 s15, s15, s27
	v_lshl_add_u64 v[18:19], s[14:15], 0, v[0:1]
	global_load_dwordx4 v[64:67], v[18:19], off
	global_load_dwordx4 v[68:71], v[18:19], off offset:1024
	global_load_dwordx4 v[72:75], v[18:19], off offset:2048
	global_load_dwordx4 v[76:79], v[18:19], off offset:3072
	s_mov_b32 s14, s4
	s_mov_b32 s15, 0
	s_lshl_b64 s[14:15], s[14:15], 11
	v_lshl_add_u64 v[20:21], v[4:5], 0, s[14:15]
	s_waitcnt vmcnt(32)
	v_pk_mul_f32 v[22:23], v[80:81], v[80:81]
	v_pk_fma_f32 v[22:23], v[82:83], v[82:83], v[22:23]
	v_pk_fma_f32 v[22:23], v[84:85], v[84:85], v[22:23]
	v_pk_fma_f32 v[22:23], v[86:87], v[86:87], v[22:23]
	v_pk_fma_f32 v[22:23], v[88:89], v[88:89], v[22:23]
	v_pk_fma_f32 v[22:23], v[90:91], v[90:91], v[22:23]
	v_pk_fma_f32 v[22:23], v[92:93], v[92:93], v[22:23]
	v_pk_fma_f32 v[22:23], v[94:95], v[94:95], v[22:23]
	s_nop 0
	v_add_f32_e32 v22, v22, v23
	ds_bpermute_b32 v26, v10, v22
	s_waitcnt lgkmcnt(0)
	v_add_f32_e32 v22, v22, v26
	ds_bpermute_b32 v26, v11, v22
	s_waitcnt lgkmcnt(0)
	v_add_f32_e32 v22, v22, v26
	ds_bpermute_b32 v26, v12, v22
	s_waitcnt lgkmcnt(0)
	v_add_f32_e32 v22, v22, v26
	ds_bpermute_b32 v26, v13, v22
	s_waitcnt lgkmcnt(0)
	v_add_f32_e32 v22, v22, v26
	ds_bpermute_b32 v26, v14, v22
	s_waitcnt lgkmcnt(0)
	v_add_f32_e32 v22, v22, v26
	ds_bpermute_b32 v26, v15, v22
	s_waitcnt lgkmcnt(0)
	v_add_f32_e32 v22, v22, v26
	v_fmamk_f32 v22, v22, 0x3a800000, v205
	v_mul_f32_e32 v26, 0x4b800000, v22
	v_cmp_gt_f32_e32 vcc, s2, v22
	s_nop 1
	v_cndmask_b32_e32 v22, v22, v26, vcc
	v_rsq_f32_e32 v22, v22
	s_nop 0
	v_mul_f32_e32 v26, 0x45800000, v22
	v_cndmask_b32_e32 v24, v22, v26, vcc
	s_waitcnt vmcnt(4)
	v_pk_mul_f32 v[80:81], v[80:81], v[24:25] op_sel_hi:[1,0]
	v_pk_mul_f32 v[82:83], v[82:83], v[24:25] op_sel_hi:[1,0]
	v_pk_add_f32 v[180:181], v[180:181], 1.0 op_sel_hi:[1,0]
	v_pk_add_f32 v[182:183], v[182:183], 1.0 op_sel_hi:[1,0]
	v_pk_fma_f32 v[80:81], v[180:181], v[80:81], v[164:165]
	v_pk_fma_f32 v[82:83], v[182:183], v[82:83], v[166:167]
	v_cvt_pk_bf16_f32 v80, v80, v81
	v_cvt_pk_bf16_f32 v81, v82, v83
	global_store_dwordx2 v[20:21], v[80:81], off
	v_pk_mul_f32 v[84:85], v[84:85], v[24:25] op_sel_hi:[1,0]
	v_pk_mul_f32 v[86:87], v[86:87], v[24:25] op_sel_hi:[1,0]
	v_pk_add_f32 v[184:185], v[184:185], 1.0 op_sel_hi:[1,0]
	v_pk_add_f32 v[186:187], v[186:187], 1.0 op_sel_hi:[1,0]
	v_pk_fma_f32 v[84:85], v[184:185], v[84:85], v[168:169]
	v_pk_fma_f32 v[86:87], v[186:187], v[86:87], v[170:171]
	v_cvt_pk_bf16_f32 v84, v84, v85
	v_cvt_pk_bf16_f32 v85, v86, v87
	global_store_dwordx2 v[20:21], v[84:85], off offset:512
	v_pk_mul_f32 v[88:89], v[88:89], v[24:25] op_sel_hi:[1,0]
	v_pk_mul_f32 v[90:91], v[90:91], v[24:25] op_sel_hi:[1,0]
	v_pk_add_f32 v[188:189], v[188:189], 1.0 op_sel_hi:[1,0]
	v_pk_add_f32 v[190:191], v[190:191], 1.0 op_sel_hi:[1,0]
	v_pk_fma_f32 v[88:89], v[188:189], v[88:89], v[172:173]
	v_pk_fma_f32 v[90:91], v[190:191], v[90:91], v[174:175]
	v_cvt_pk_bf16_f32 v88, v88, v89
	v_cvt_pk_bf16_f32 v89, v90, v91
	global_store_dwordx2 v[20:21], v[88:89], off offset:1024
	v_pk_mul_f32 v[92:93], v[92:93], v[24:25] op_sel_hi:[1,0]
	v_pk_mul_f32 v[94:95], v[94:95], v[24:25] op_sel_hi:[1,0]
	v_pk_add_f32 v[192:193], v[192:193], 1.0 op_sel_hi:[1,0]
	v_pk_add_f32 v[194:195], v[194:195], 1.0 op_sel_hi:[1,0]
	v_pk_fma_f32 v[92:93], v[192:193], v[92:93], v[176:177]
	v_pk_fma_f32 v[94:95], v[194:195], v[94:95], v[178:179]
	v_cvt_pk_bf16_f32 v92, v92, v93
	v_cvt_pk_bf16_f32 v93, v94, v95
	global_store_dwordx2 v[20:21], v[92:93], off offset:1536
	s_add_i32 s4, s4, s62
	s_cmp_ge_i32 s4, 0x8000
	s_cbranch_scc1 .Lp1_done
	s_branch .Lp1_loop
.Lp1_done:
	s_mov_b32 s5, 0
	s_lshl_b64 s[6:7], s[4:5], 12
	s_cmp_gt_i32 s4, 0x87ff
	s_cbranch_scc1 .LBB0_100
.Lp1_skip:
	s_branch .LBB0_93

; __global__ void __launch_bounds__(512, 2) mega_fwd(Args a) {
;     ...
;     { PHASE_IDS();
;     for (int m = gw; m < TL; m += NGW) {
;         f32x4* xr = (f32x4*)(OUTP + (size_t)m * DM) + lane;
;         f32x4 v[4]; float s = 0.f;
; #pragma unroll
;         for (int j = 0; j < 4; ++j) { v[j] = xr[64 * j]; s += (v[j].x * v[j].x + v[j].y * v[j].y) + (v[j].z * v[j].z + v[j].w * v[j].w); }
;         const float rstd = rsqrtf(wave_sum(s, lane) * (1.f / DM) + EPS);
; #pragma unroll
;         for (int j = 0; j < 4; ++j) xr[64 * j] = v[j] * rstd * ((const f32x4*)IN(I_FG))[lane + 64 * j];
;     }
.LBB0_971:
	v_readlane_b32 s4, v252, 3
	s_cmpk_gt_i32 s8, 0x7fff
	v_readlane_b32 s5, v252, 4
	v_mbcnt_lo_u32_b32 v0, -1, 0
	v_mbcnt_hi_u32_b32 v0, -1, v0
	s_cbranch_scc1 .LBB0_974
	s_load_dwordx4 s[0:3], s[4:5], 0xb8
	v_ashrrev_i32_e32 v1, 31, v0
	v_lshlrev_b32_e32 v2, 2, v0
	v_xor_b32_e32 v4, 4, v2
	v_xor_b32_e32 v5, 8, v2
	v_xor_b32_e32 v6, 16, v2
	v_xor_b32_e32 v7, 32, v2
	v_xor_b32_e32 v8, 64, v2
	v_xor_b32_e32 v9, 0x80, v2
	v_lshlrev_b64 v[2:3], 4, v[0:1]
	s_ashr_i32 s9, s8, 31
	s_waitcnt lgkmcnt(0)
	v_lshl_add_u64 v[0:1], s[0:1], 0, v[2:3]
	global_load_dwordx4 v[112:115], v[0:1], off
	global_load_dwordx4 v[116:119], v[0:1], off offset:1024
	global_load_dwordx4 v[120:123], v[0:1], off offset:2048
	global_load_dwordx4 v[124:127], v[0:1], off offset:3072
	v_mov_b32_e32 v10, 0x358637bd
	s_mov_b32 s0, 0x800000
	s_mov_b32 s4, s8
	s_mov_b32 s5, 0
	s_lshl_b64 s[4:5], s[4:5], 12
	s_add_u32 s4, s4, s2
	s_addc_u32 s5, s5, s3
	v_lshl_add_u64 v[12:13], s[4:5], 0, v[2:3]
	global_load_dwordx4 v[64:67], v[12:13], off
	global_load_dwordx4 v[68:71], v[12:13], off offset:1024
	global_load_dwordx4 v[72:75], v[12:13], off offset:2048
	global_load_dwordx4 v[76:79], v[12:13], off offset:3072
	s_add_i32 s9, s8, s62
	s_cmp_lt_i32 s9, 0x8000
	s_cselect_b32 s9, s9, s8
	s_mov_b32 s4, s9
	s_mov_b32 s5, 0
	s_lshl_b64 s[4:5], s[4:5], 12
	s_add_u32 s4, s4, s2
	s_addc_u32 s5, s5, s3
	v_lshl_add_u64 v[12:13], s[4:5], 0, v[2:3]
	global_load_dwordx4 v[80:83], v[12:13], off
	global_load_dwordx4 v[84:87], v[12:13], off offset:1024
	global_load_dwordx4 v[88:91], v[12:13], off offset:2048
	global_load_dwordx4 v[92:95], v[12:13], off offset:3072
	s_add_i32 s9, s8, s62
	s_add_i32 s9, s9, s62
	s_cmp_lt_i32 s9, 0x8000
	s_cselect_b32 s9, s9, s8
	s_mov_b32 s4, s9
	s_mov_b32 s5, 0
	s_lshl_b64 s[4:5], s[4:5], 12
	s_add_u32 s4, s4, s2
	s_addc_u32 s5, s5, s3
	v_lshl_add_u64 v[12:13], s[4:5], 0, v[2:3]
	global_load_dwordx4 v[96:99], v[12:13], off
	global_load_dwordx4 v[100:103], v[12:13], off offset:1024
	global_load_dwordx4 v[104:107], v[12:13], off offset:2048
	global_load_dwordx4 v[108:111], v[12:13], off offset:3072
	s_mov_b32 s4, s8
	s_mov_b32 s5, 0
	s_lshl_b64 s[4:5], s[4:5], 12
	s_add_u32 s4, s4, s2
	s_addc_u32 s5, s5, s3
	v_lshl_add_u64 v[14:15], s[4:5], 0, v[2:3]
	s_waitcnt vmcnt(8)
	v_pk_mul_f32 v[16:17], v[64:65], v[64:65]
	v_pk_fma_f32 v[16:17], v[66:67], v[66:67], v[16:17]
	v_pk_fma_f32 v[16:17], v[68:69], v[68:69], v[16:17]
	v_pk_fma_f32 v[16:17], v[70:71], v[70:71], v[16:17]
	v_pk_fma_f32 v[16:17], v[72:73], v[72:73], v[16:17]
	v_pk_fma_f32 v[16:17], v[74:75], v[74:75], v[16:17]
	v_pk_fma_f32 v[16:17], v[76:77], v[76:77], v[16:17]
	v_pk_fma_f32 v[16:17], v[78:79], v[78:79], v[16:17]
	s_nop 0
	v_add_f32_e32 v16, v16, v17
	ds_bpermute_b32 v18, v4, v16
	s_waitcnt lgkmcnt(0)
	v_add_f32_e32 v16, v16, v18
	ds_bpermute_b32 v18, v5, v16
	s_waitcnt lgkmcnt(0)
	v_add_f32_e32 v16, v16, v18
	ds_bpermute_b32 v18, v6, v16
	s_waitcnt lgkmcnt(0)
	v_add_f32_e32 v16, v16, v18
	ds_bpermute_b32 v18, v7, v16
	s_waitcnt lgkmcnt(0)
	v_add_f32_e32 v16, v16, v18
	ds_bpermute_b32 v18, v8, v16
	s_waitcnt lgkmcnt(0)
	v_add_f32_e32 v16, v16, v18
	ds_bpermute_b32 v18, v9, v16
	s_waitcnt lgkmcnt(0)
	v_add_f32_e32 v16, v16, v18
	v_fmamk_f32 v16, v16, 0x3a800000, v10
	v_mul_f32_e32 v18, 0x4b800000, v16
	v_cmp_gt_f32_e32 vcc, s0, v16
	s_nop 1
	v_cndmask_b32_e32 v16, v16, v18, vcc
	v_rsq_f32_e32 v16, v16
	s_nop 0
	v_mul_f32_e32 v18, 0x45800000, v16
	v_cndmask_b32_e32 v20, v16, v18, vcc
	v_pk_mul_f32 v[64:65], v[64:65], v[20:21] op_sel_hi:[1,0]
	v_pk_mul_f32 v[66:67], v[66:67], v[20:21] op_sel_hi:[1,0]
	v_pk_mul_f32 v[64:65], v[64:65], v[112:113]
	v_pk_mul_f32 v[66:67], v[66:67], v[114:115]
	global_store_dwordx4 v[14:15], v[64:67], off
	v_pk_mul_f32 v[68:69], v[68:69], v[20:21] op_sel_hi:[1,0]
	v_pk_mul_f32 v[70:71], v[70:71], v[20:21] op_sel_hi:[1,0]
	v_pk_mul_f32 v[68:69], v[68:69], v[116:117]
	v_pk_mul_f32 v[70:71], v[70:71], v[118:119]
	global_store_dwordx4 v[14:15], v[68:71], off offset:1024
	v_pk_mul_f32 v[72:73], v[72:73], v[20:21] op_sel_hi:[1,0]
	v_pk_mul_f32 v[74:75], v[74:75], v[20:21] op_sel_hi:[1,0]
	v_pk_mul_f32 v[72:73], v[72:73], v[120:121]
	v_pk_mul_f32 v[74:75], v[74:75], v[122:123]
	global_store_dwordx4 v[14:15], v[72:75], off offset:2048
	v_pk_mul_f32 v[76:77], v[76:77], v[20:21] op_sel_hi:[1,0]
	v_pk_mul_f32 v[78:79], v[78:79], v[20:21] op_sel_hi:[1,0]
	v_pk_mul_f32 v[76:77], v[76:77], v[124:125]
	v_pk_mul_f32 v[78:79], v[78:79], v[126:127]
	global_store_dwordx4 v[14:15], v[76:79], off offset:3072
	s_add_i32 s8, s8, s62
	s_cmp_ge_i32 s8, 0x8000
	s_cbranch_scc1 .Lfin_done
; __global__ void __launch_bounds__(512, 2) mega_fwd(Args a) {
;     ...
;     { PHASE_IDS();
;     for (int m = gw; m < TL; m += NGW) {
;         f32x4* xr = (f32x4*)(OUTP + (size_t)m * DM) + lane;
;         f32x4 v[4]; float s = 0.f;
; #pragma unroll
;         for (int j = 0; j < 4; ++j) { v[j] = xr[64 * j]; s += (v[j].x * v[j].x + v[j].y * v[j].y) + (v[j].z * v[j].z + v[j].w * v[j].w); }
;         const float rstd = rsqrtf(wave_sum(s, lane) * (1.f / DM) + EPS);
; #pragma unroll
;         for (int j = 0; j < 4; ++j) xr[64 * j] = v[j] * rstd * ((const f32x4*)IN(I_FG))[lane + 64 * j];
;     }
	s_add_i32 s9, s8, s62
	s_add_i32 s9, s9, s62
	s_cmp_lt_i32 s9, 0x8000
	s_cselect_b32 s9, s9, s8
	s_mov_b32 s4, s9
	s_mov_b32 s5, 0
	s_lshl_b64 s[4:5], s[4:5], 12
	s_add_u32 s4, s4, s2
	s_addc_u32 s5, s5, s3
	v_lshl_add_u64 v[12:13], s[4:5], 0, v[2:3]
	global_load_dwordx4 v[64:67], v[12:13], off
	global_load_dwordx4 v[68:71], v[12:13], off offset:1024
	global_load_dwordx4 v[72:75], v[12:13], off offset:2048
	global_load_dwordx4 v[76:79], v[12:13], off offset:3072
	s_mov_b32 s4, s8
	s_mov_b32 s5, 0
	s_lshl_b64 s[4:5], s[4:5], 12
	s_add_u32 s4, s4, s2
	s_addc_u32 s5, s5, s3
	v_lshl_add_u64 v[14:15], s[4:5], 0, v[2:3]
	s_waitcnt vmcnt(12)
	v_pk_mul_f32 v[16:17], v[80:81], v[80:81]
	v_pk_fma_f32 v[16:17], v[82:83], v[82:83], v[16:17]
	v_pk_fma_f32 v[16:17], v[84:85], v[84:85], v[16:17]
	v_pk_fma_f32 v[16:17], v[86:87], v[86:87], v[16:17]
	v_pk_fma_f32 v[16:17], v[88:89], v[88:89], v[16:17]
	v_pk_fma_f32 v[16:17], v[90:91], v[90:91], v[16:17]
	v_pk_fma_f32 v[16:17], v[92:93], v[92:93], v[16:17]
	v_pk_fma_f32 v[16:17], v[94:95], v[94:95], v[16:17]
	s_nop 0
	v_add_f32_e32 v16, v16, v17
	ds_bpermute_b32 v18, v4, v16
	s_waitcnt lgkmcnt(0)
	v_add_f32_e32 v16, v16, v18
	ds_bpermute_b32 v18, v5, v16
	s_waitcnt lgkmcnt(0)
	v_add_f32_e32 v16, v16, v18
	ds_bpermute_b32 v18, v6, v16
	s_waitcnt lgkmcnt(0)
	v_add_f32_e32 v16, v16, v18
	ds_bpermute_b32 v18, v7, v16
	s_waitcnt lgkmcnt(0)
	v_add_f32_e32 v16, v16, v18
	ds_bpermute_b32 v18, v8, v16
	s_waitcnt lgkmcnt(0)
	v_add_f32_e32 v16, v16, v18
	ds_bpermute_b32 v18, v9, v16
	s_waitcnt lgkmcnt(0)
	v_add_f32_e32 v16, v16, v18
	v_fmamk_f32 v16, v16, 0x3a800000, v10
	v_mul_f32_e32 v18, 0x4b800000, v16
	v_cmp_gt_f32_e32 vcc, s0, v16
	s_nop 1
	v_cndmask_b32_e32 v16, v16, v18, vcc
	v_rsq_f32_e32 v16, v16
	s_nop 0
	v_mul_f32_e32 v18, 0x45800000, v16
	v_cndmask_b32_e32 v20, v16, v18, vcc
	v_pk_mul_f32 v[80:81], v[80:81], v[20:21] op_sel_hi:[1,0]
	v_pk_mul_f32 v[82:83], v[82:83], v[20:21] op_sel_hi:[1,0]
	v_pk_mul_f32 v[80:81], v[80:81], v[112:113]
	v_pk_mul_f32 v[82:83], v[82:83], v[114:115]
	global_store_dwordx4 v[14:15], v[80:83], off
	v_pk_mul_f32 v[84:85], v[84:85], v[20:21] op_sel_hi:[1,0]
	v_pk_mul_f32 v[86:87], v[86:87], v[20:21] op_sel_hi:[1,0]
	v_pk_mul_f32 v[84:85], v[84:85], v[116:117]
	v_pk_mul_f32 v[86:87], v[86:87], v[118:119]
	global_store_dwordx4 v[14:15], v[84:87], off offset:1024
	v_pk_mul_f32 v[88:89], v[88:89], v[20:21] op_sel_hi:[1,0]
	v_pk_mul_f32 v[90:91], v[90:91], v[20:21] op_sel_hi:[1,0]
	v_pk_mul_f32 v[88:89], v[88:89], v[120:121]
	v_pk_mul_f32 v[90:91], v[90:91], v[122:123]
	global_store_dwordx4 v[14:15], v[88:91], off offset:2048
	v_pk_mul_f32 v[92:93], v[92:93], v[20:21] op_sel_hi:[1,0]
	v_pk_mul_f32 v[94:95], v[94:95], v[20:21] op_sel_hi:[1,0]
	v_pk_mul_f32 v[92:93], v[92:93], v[124:125]
	v_pk_mul_f32 v[94:95], v[94:95], v[126:127]
	global_store_dwordx4 v[14:15], v[92:95], off offset:3072
	s_add_i32 s8, s8, s62
	s_cmp_ge_i32 s8, 0x8000
	s_cbranch_scc1 .Lfin_done
.Lfin_loop:
	s_add_i32 s9, s8, s62
	s_add_i32 s9, s9, s62
	s_cmp_lt_i32 s9, 0x8000
	s_cselect_b32 s9, s9, s8
	s_mov_b32 s4, s9
	s_mov_b32 s5, 0
	s_lshl_b64 s[4:5], s[4:5], 12
	s_add_u32 s4, s4, s2
	s_addc_u32 s5, s5, s3
	v_lshl_add_u64 v[12:13], s[4:5], 0, v[2:3]
	global_load_dwordx4 v[80:83], v[12:13], off
	global_load_dwordx4 v[84:87], v[12:13], off offset:1024
	global_load_dwordx4 v[88:91], v[12:13], off offset:2048
	global_load_dwordx4 v[92:95], v[12:13], off offset:3072
	s_mov_b32 s4, s8
	s_mov_b32 s5, 0
	s_lshl_b64 s[4:5], s[4:5], 12
	s_add_u32 s4, s4, s2
	s_addc_u32 s5, s5, s3
	v_lshl_add_u64 v[14:15], s[4:5], 0, v[2:3]
	s_waitcnt vmcnt(16)
	v_pk_mul_f32 v[16:17], v[96:97], v[96:97]
	v_pk_fma_f32 v[16:17], v[98:99], v[98:99], v[16:17]
	v_pk_fma_f32 v[16:17], v[100:101], v[100:101], v[16:17]
	v_pk_fma_f32 v[16:17], v[102:103], v[102:103], v[16:17]
	v_pk_fma_f32 v[16:17], v[104:105], v[104:105], v[16:17]
	v_pk_fma_f32 v[16:17], v[106:107], v[106:107], v[16:17]
	v_pk_fma_f32 v[16:17], v[108:109], v[108:109], v[16:17]
	v_pk_fma_f32 v[16:17], v[110:111], v[110:111], v[16:17]
	s_nop 0
	v_add_f32_e32 v16, v16, v17
	ds_bpermute_b32 v18, v4, v16
	s_waitcnt lgkmcnt(0)
	v_add_f32_e32 v16, v16, v18
	ds_bpermute_b32 v18, v5, v16
	s_waitcnt lgkmcnt(0)
	v_add_f32_e32 v16, v16, v18
	ds_bpermute_b32 v18, v6, v16
	s_waitcnt lgkmcnt(0)
	v_add_f32_e32 v16, v16, v18
	ds_bpermute_b32 v18, v7, v16
	s_waitcnt lgkmcnt(0)
	v_add_f32_e32 v16, v16, v18
	ds_bpermute_b32 v18, v8, v16
	s_waitcnt lgkmcnt(0)
	v_add_f32_e32 v16, v16, v18
	ds_bpermute_b32 v18, v9, v16
	s_waitcnt lgkmcnt(0)
	v_add_f32_e32 v16, v16, v18
	v_fmamk_f32 v16, v16, 0x3a800000, v10
	v_mul_f32_e32 v18, 0x4b800000, v16
	v_cmp_gt_f32_e32 vcc, s0, v16
	s_nop 1
	v_cndmask_b32_e32 v16, v16, v18, vcc
	v_rsq_f32_e32 v16, v16
	s_nop 0
	v_mul_f32_e32 v18, 0x45800000, v16
	v_cndmask_b32_e32 v20, v16, v18, vcc
	v_pk_mul_f32 v[96:97], v[96:97], v[20:21] op_sel_hi:[1,0]
	v_pk_mul_f32 v[98:99], v[98:99], v[20:21] op_sel_hi:[1,0]
	v_pk_mul_f32 v[96:97], v[96:97], v[112:113]
	v_pk_mul_f32 v[98:99], v[98:99], v[114:115]
	global_store_dwordx4 v[14:15], v[96:99], off
	v_pk_mul_f32 v[100:101], v[100:101], v[20:21] op_sel_hi:[1,0]
	v_pk_mul_f32 v[102:103], v[102:103], v[20:21] op_sel_hi:[1,0]
	v_pk_mul_f32 v[100:101], v[100:101], v[116:117]
	v_pk_mul_f32 v[102:103], v[102:103], v[118:119]
	global_store_dwordx4 v[14:15], v[100:103], off offset:1024
	v_pk_mul_f32 v[104:105], v[104:105], v[20:21] op_sel_hi:[1,0]
	v_pk_mul_f32 v[106:107], v[106:107], v[20:21] op_sel_hi:[1,0]
	v_pk_mul_f32 v[104:105], v[104:105], v[120:121]
	v_pk_mul_f32 v[106:107], v[106:107], v[122:123]
	global_store_dwordx4 v[14:15], v[104:107], off offset:2048
	v_pk_mul_f32 v[108:109], v[108:109], v[20:21] op_sel_hi:[1,0]
	v_pk_mul_f32 v[110:111], v[110:111], v[20:21] op_sel_hi:[1,0]
	v_pk_mul_f32 v[108:109], v[108:109], v[124:125]
	v_pk_mul_f32 v[110:111], v[110:111], v[126:127]
	global_store_dwordx4 v[14:15], v[108:111], off offset:3072
	s_add_i32 s8, s8, s62
	s_cmp_ge_i32 s8, 0x8000
	s_cbranch_scc1 .Lfin_done
; __global__ void __launch_bounds__(512, 2) mega_fwd(Args a) {
;     ...
;     { PHASE_IDS();
;     for (int m = gw; m < TL; m += NGW) {
;         f32x4* xr = (f32x4*)(OUTP + (size_t)m * DM) + lane;
;         f32x4 v[4]; float s = 0.f;
; #pragma unroll
;         for (int j = 0; j < 4; ++j) { v[j] = xr[64 * j]; s += (v[j].x * v[j].x + v[j].y * v[j].y) + (v[j].z * v[j].z + v[j].w * v[j].w); }
;         const float rstd = rsqrtf(wave_sum(s, lane) * (1.f / DM) + EPS);
; #pragma unroll
;         for (int j = 0; j < 4; ++j) xr[64 * j] = v[j] * rstd * ((const f32x4*)IN(I_FG))[lane + 64 * j];
;     }
	s_add_i32 s9, s8, s62
	s_add_i32 s9, s9, s62
	s_cmp_lt_i32 s9, 0x8000
	s_cselect_b32 s9, s9, s8
	s_mov_b32 s4, s9
	s_mov_b32 s5, 0
	s_lshl_b64 s[4:5], s[4:5], 12
	s_add_u32 s4, s4, s2
	s_addc_u32 s5, s5, s3
	v_lshl_add_u64 v[12:13], s[4:5], 0, v[2:3]
	global_load_dwordx4 v[96:99], v[12:13], off
	global_load_dwordx4 v[100:103], v[12:13], off offset:1024
	global_load_dwordx4 v[104:107], v[12:13], off offset:2048
	global_load_dwordx4 v[108:111], v[12:13], off offset:3072
	s_mov_b32 s4, s8
	s_mov_b32 s5, 0
	s_lshl_b64 s[4:5], s[4:5], 12
	s_add_u32 s4, s4, s2
	s_addc_u32 s5, s5, s3
	v_lshl_add_u64 v[14:15], s[4:5], 0, v[2:3]
	s_waitcnt vmcnt(16)
	v_pk_mul_f32 v[16:17], v[64:65], v[64:65]
	v_pk_fma_f32 v[16:17], v[66:67], v[66:67], v[16:17]
	v_pk_fma_f32 v[16:17], v[68:69], v[68:69], v[16:17]
	v_pk_fma_f32 v[16:17], v[70:71], v[70:71], v[16:17]
	v_pk_fma_f32 v[16:17], v[72:73], v[72:73], v[16:17]
	v_pk_fma_f32 v[16:17], v[74:75], v[74:75], v[16:17]
	v_pk_fma_f32 v[16:17], v[76:77], v[76:77], v[16:17]
	v_pk_fma_f32 v[16:17], v[78:79], v[78:79], v[16:17]
	s_nop 0
	v_add_f32_e32 v16, v16, v17
	ds_bpermute_b32 v18, v4, v16
	s_waitcnt lgkmcnt(0)
	v_add_f32_e32 v16, v16, v18
	ds_bpermute_b32 v18, v5, v16
	s_waitcnt lgkmcnt(0)
	v_add_f32_e32 v16, v16, v18
	ds_bpermute_b32 v18, v6, v16
	s_waitcnt lgkmcnt(0)
	v_add_f32_e32 v16, v16, v18
	ds_bpermute_b32 v18, v7, v16
	s_waitcnt lgkmcnt(0)
	v_add_f32_e32 v16, v16, v18
	ds_bpermute_b32 v18, v8, v16
	s_waitcnt lgkmcnt(0)
	v_add_f32_e32 v16, v16, v18
	ds_bpermute_b32 v18, v9, v16
	s_waitcnt lgkmcnt(0)
	v_add_f32_e32 v16, v16, v18
	v_fmamk_f32 v16, v16, 0x3a800000, v10
	v_mul_f32_e32 v18, 0x4b800000, v16
	v_cmp_gt_f32_e32 vcc, s0, v16
	s_nop 1
	v_cndmask_b32_e32 v16, v16, v18, vcc
	v_rsq_f32_e32 v16, v16
	s_nop 0
	v_mul_f32_e32 v18, 0x45800000, v16
	v_cndmask_b32_e32 v20, v16, v18, vcc
	v_pk_mul_f32 v[64:65], v[64:65], v[20:21] op_sel_hi:[1,0]
	v_pk_mul_f32 v[66:67], v[66:67], v[20:21] op_sel_hi:[1,0]
	v_pk_mul_f32 v[64:65], v[64:65], v[112:113]
	v_pk_mul_f32 v[66:67], v[66:67], v[114:115]
	global_store_dwordx4 v[14:15], v[64:67], off
	v_pk_mul_f32 v[68:69], v[68:69], v[20:21] op_sel_hi:[1,0]
	v_pk_mul_f32 v[70:71], v[70:71], v[20:21] op_sel_hi:[1,0]
	v_pk_mul_f32 v[68:69], v[68:69], v[116:117]
	v_pk_mul_f32 v[70:71], v[70:71], v[118:119]
	global_store_dwordx4 v[14:15], v[68:71], off offset:1024
	v_pk_mul_f32 v[72:73], v[72:73], v[20:21] op_sel_hi:[1,0]
	v_pk_mul_f32 v[74:75], v[74:75], v[20:21] op_sel_hi:[1,0]
	v_pk_mul_f32 v[72:73], v[72:73], v[120:121]
	v_pk_mul_f32 v[74:75], v[74:75], v[122:123]
	global_store_dwordx4 v[14:15], v[72:75], off offset:2048
	v_pk_mul_f32 v[76:77], v[76:77], v[20:21] op_sel_hi:[1,0]
	v_pk_mul_f32 v[78:79], v[78:79], v[20:21] op_sel_hi:[1,0]
	v_pk_mul_f32 v[76:77], v[76:77], v[124:125]
	v_pk_mul_f32 v[78:79], v[78:79], v[126:127]
	global_store_dwordx4 v[14:15], v[76:79], off offset:3072
	s_add_i32 s8, s8, s62
	s_cmp_ge_i32 s8, 0x8000
	s_cbranch_scc1 .Lfin_done
	s_add_i32 s9, s8, s62
	s_add_i32 s9, s9, s62
	s_cmp_lt_i32 s9, 0x8000
	s_cselect_b32 s9, s9, s8
	s_mov_b32 s4, s9
	s_mov_b32 s5, 0
	s_lshl_b64 s[4:5], s[4:5], 12
	s_add_u32 s4, s4, s2
	s_addc_u32 s5, s5, s3
	v_lshl_add_u64 v[12:13], s[4:5], 0, v[2:3]
	global_load_dwordx4 v[64:67], v[12:13], off
	global_load_dwordx4 v[68:71], v[12:13], off offset:1024
	global_load_dwordx4 v[72:75], v[12:13], off offset:2048
	global_load_dwordx4 v[76:79], v[12:13], off offset:3072
	s_mov_b32 s4, s8
	s_mov_b32 s5, 0
	s_lshl_b64 s[4:5], s[4:5], 12
	s_add_u32 s4, s4, s2
	s_addc_u32 s5, s5, s3
	v_lshl_add_u64 v[14:15], s[4:5], 0, v[2:3]
	s_waitcnt vmcnt(16)
	v_pk_mul_f32 v[16:17], v[80:81], v[80:81]
	v_pk_fma_f32 v[16:17], v[82:83], v[82:83], v[16:17]
	v_pk_fma_f32 v[16:17], v[84:85], v[84:85], v[16:17]
	v_pk_fma_f32 v[16:17], v[86:87], v[86:87], v[16:17]
	v_pk_fma_f32 v[16:17], v[88:89], v[88:89], v[16:17]
	v_pk_fma_f32 v[16:17], v[90:91], v[90:91], v[16:17]
	v_pk_fma_f32 v[16:17], v[92:93], v[92:93], v[16:17]
	v_pk_fma_f32 v[16:17], v[94:95], v[94:95], v[16:17]
	s_nop 0
	v_add_f32_e32 v16, v16, v17
	ds_bpermute_b32 v18, v4, v16
	s_waitcnt lgkmcnt(0)
	v_add_f32_e32 v16, v16, v18
	ds_bpermute_b32 v18, v5, v16
	s_waitcnt lgkmcnt(0)
	v_add_f32_e32 v16, v16, v18
	ds_bpermute_b32 v18, v6, v16
	s_waitcnt lgkmcnt(0)
	v_add_f32_e32 v16, v16, v18
	ds_bpermute_b32 v18, v7, v16
	s_waitcnt lgkmcnt(0)
	v_add_f32_e32 v16, v16, v18
	ds_bpermute_b32 v18, v8, v16
	s_waitcnt lgkmcnt(0)
	v_add_f32_e32 v16, v16, v18
	ds_bpermute_b32 v18, v9, v16
	s_waitcnt lgkmcnt(0)
	v_add_f32_e32 v16, v16, v18
	v_fmamk_f32 v16, v16, 0x3a800000, v10
	v_mul_f32_e32 v18, 0x4b800000, v16
	v_cmp_gt_f32_e32 vcc, s0, v16
	s_nop 1
	v_cndmask_b32_e32 v16, v16, v18, vcc
	v_rsq_f32_e32 v16, v16
	s_nop 0
	v_mul_f32_e32 v18, 0x45800000, v16
	v_cndmask_b32_e32 v20, v16, v18, vcc
	v_pk_mul_f32 v[80:81], v[80:81], v[20:21] op_sel_hi:[1,0]
	v_pk_mul_f32 v[82:83], v[82:83], v[20:21] op_sel_hi:[1,0]
	v_pk_mul_f32 v[80:81], v[80:81], v[112:113]
	v_pk_mul_f32 v[82:83], v[82:83], v[114:115]
	global_store_dwordx4 v[14:15], v[80:83], off
	v_pk_mul_f32 v[84:85], v[84:85], v[20:21] op_sel_hi:[1,0]
	v_pk_mul_f32 v[86:87], v[86:87], v[20:21] op_sel_hi:[1,0]
	v_pk_mul_f32 v[84:85], v[84:85], v[116:117]
	v_pk_mul_f32 v[86:87], v[86:87], v[118:119]
	global_store_dwordx4 v[14:15], v[84:87], off offset:1024
	v_pk_mul_f32 v[88:89], v[88:89], v[20:21] op_sel_hi:[1,0]
	v_pk_mul_f32 v[90:91], v[90:91], v[20:21] op_sel_hi:[1,0]
	v_pk_mul_f32 v[88:89], v[88:89], v[120:121]
	v_pk_mul_f32 v[90:91], v[90:91], v[122:123]
	global_store_dwordx4 v[14:15], v[88:91], off offset:2048
	v_pk_mul_f32 v[92:93], v[92:93], v[20:21] op_sel_hi:[1,0]
	v_pk_mul_f32 v[94:95], v[94:95], v[20:21] op_sel_hi:[1,0]
	v_pk_mul_f32 v[92:93], v[92:93], v[124:125]
	v_pk_mul_f32 v[94:95], v[94:95], v[126:127]
	global_store_dwordx4 v[14:15], v[92:95], off offset:3072
	s_add_i32 s8, s8, s62
	s_cmp_ge_i32 s8, 0x8000
	s_cbranch_scc1 .Lfin_done
	s_branch .Lfin_loop
.Lfin_done:
.LBB0_974:
	s_endpgm
